# attention loops: back-edge rotation (sec 7.11) - global-load issue and guard/address block moved in front of the step barriers, barriers relocated to the first ds_read
# speedup vs baseline: 1.0023x; 1.0023x over previous
.LBB0_511:
	v_mul_u32_u24_e32 v174, 0x90, v8
	v_bfe_u32 v8, v6, 2, 2
	v_lshl_add_u64 v[0:1], s[2:3], 0, v[0:1]
	v_and_b32_e32 v173, 63, v6
	s_lshl_b32 s44, s84, 6
	v_lshlrev_b32_e32 v172, 3, v7
	v_lshl_or_b32 v7, v7, 2, v8
	v_and_b32_e32 v8, 16, v6
	v_lshlrev_b32_e32 v6, 2, v6
	v_lshl_add_u64 v[0:1], v[2:3], 1, v[0:1]
	v_mul_u32_u24_e32 v7, 0xc0, v7
	v_and_or_b32 v6, v6, 12, v8
	s_and_b64 s[4:5], s[6:7], exec
	v_lshl_add_u64 v[156:157], s[74:75], 0, v[0:1]
	v_lshl_add_u64 v[0:1], s[2:3], 0, v[4:5]
	v_lshlrev_b32_e32 v6, 1, v6
	s_cselect_b32 s0, 4, 0x44
	v_add_u32_e32 v7, 0, v7
	s_lshl_b32 s1, s1, 5
	v_lshl_add_u64 v[0:1], v[0:1], 0, v[128:129]
	v_lshlrev_b32_e32 v170, 3, v9
	s_and_b32 s38, s1, 0x80
	s_mov_b32 s39, s93
	v_lshl_add_u64 v[158:159], s[74:75], 0, v[0:1]
	s_mov_b32 s1, 3
	v_add_u32_e32 v175, v7, v6
	v_mov_b32_e32 v33, v32
	v_mov_b32_e32 v34, v32
	v_mov_b32_e32 v35, v32
	v_mov_b32_e32 v36, v32
	v_mov_b32_e32 v37, v32
	v_mov_b32_e32 v38, v32
	v_mov_b32_e32 v39, v32
	v_mov_b32_e32 v40, v32
	v_mov_b32_e32 v41, v32
	v_mov_b32_e32 v42, v32
	v_mov_b32_e32 v43, v32
	v_mov_b32_e32 v44, v32
	v_mov_b32_e32 v45, v32
	v_mov_b32_e32 v46, v32
	v_mov_b32_e32 v47, v32
	v_mov_b32_e32 v16, v176
	v_mov_b32_e32 v17, v176
	v_mov_b32_e32 v18, v176
	v_mov_b32_e32 v19, v176
	v_mov_b32_e32 v20, v176
	v_mov_b32_e32 v21, v176
	v_mov_b32_e32 v22, v176
	v_mov_b32_e32 v23, v176
	v_mov_b32_e32 v24, v176
	v_mov_b32_e32 v25, v176
	v_mov_b32_e32 v26, v176
	v_mov_b32_e32 v27, v176
	v_mov_b32_e32 v28, v176
	v_mov_b32_e32 v29, v176
	v_mov_b32_e32 v30, v176
	v_mov_b32_e32 v31, v176
	v_mov_b32_e32 v0, v176
	v_mov_b32_e32 v1, v176
	v_mov_b32_e32 v2, v176
	v_mov_b32_e32 v3, v176
	v_mov_b32_e32 v4, v176
	v_mov_b32_e32 v5, v176
	v_mov_b32_e32 v6, v176
	v_mov_b32_e32 v7, v176
	v_mov_b32_e32 v8, v176
	v_mov_b32_e32 v9, v176
	v_mov_b32_e32 v10, v176
	v_mov_b32_e32 v11, v176
	v_mov_b32_e32 v12, v176
	v_mov_b32_e32 v13, v176
	v_mov_b32_e32 v14, v176
	v_mov_b32_e32 v15, v176
	s_branch .LBB0_513
.LBB0_512:
	s_add_i32 s1, s1, 2
	v_lshl_add_u64 v[156:157], v[156:157], 0, s[94:95]
	s_cmp_lt_u32 s80, s0
	v_lshl_add_u64 v[158:159], v[158:159], 0, s[94:95]
	s_waitcnt lgkmcnt(0)
	s_cbranch_scc1 .Lrot1a_c
	s_barrier
	s_branch .LBB0_535
.Lrot1a_c:
.LBB0_513:
	s_add_i32 s80, s1, -1
	s_cmp_lt_u32 s80, s0
	s_cselect_b64 s[40:41], -1, 0
	s_cmp_ge_u32 s80, s0
	v_lshl_add_u64 v[160:161], v[156:157], 0, s[38:39]
	s_cbranch_scc1 .LBB0_515
	v_add_co_u32_e32 v80, vcc, 0x6dd0000, v160
	s_nop 1
	v_addc_co_u32_e32 v81, vcc, 0, v161, vcc
	global_load_dwordx4 v[142:145], v[80:81], off offset:1856

.LBB0_517:
	s_barrier
	ds_read_b128 v[112:115], v165 offset:9216
	ds_read_b128 v[116:119], v165 offset:9248
	v_exp_f32_e32 v206, v48
	v_exp_f32_e32 v208, v49
	v_exp_f32_e32 v210, v50
	v_exp_f32_e32 v212, v51
	v_exp_f32_e32 v214, v52
	v_exp_f32_e32 v216, v53
	v_exp_f32_e32 v218, v54
	s_waitcnt lgkmcnt(1)
	v_mfma_f32_32x32x16_bf16 v[96:111], v[112:115], v[130:133], v[32:47]
	ds_read_b128 v[178:181], v165 offset:13824
	ds_read_b128 v[182:185], v165 offset:13856
	ds_read_b128 v[112:115], v165 offset:9280
	ds_read_b128 v[194:197], v165 offset:9312
	ds_read_b128 v[198:201], v165 offset:13888
	ds_read_b128 v[202:205], v165 offset:13920
	v_exp_f32_e32 v220, v55
	ds_read_b64_tr_b16 v[48:49], v175 offset:18432
	ds_read_b64_tr_b16 v[50:51], v175 offset:19968
	ds_read_b64_tr_b16 v[54:55], v175 offset:20032
	ds_read_b64_tr_b16 v[52:53], v175 offset:18496
	v_exp_f32_e32 v222, v66
	v_exp_f32_e32 v224, v67
	v_cvt_pk_bf16_f32 v66, v214, v216
	v_cvt_pk_bf16_f32 v67, v218, v220
	s_waitcnt lgkmcnt(10)
	v_mfma_f32_32x32x16_bf16 v[96:111], v[116:119], v[134:137], v[96:111]
	v_exp_f32_e32 v207, v56
	v_exp_f32_e32 v209, v57
	v_exp_f32_e32 v211, v58
	v_exp_f32_e32 v213, v59
	v_exp_f32_e32 v215, v60
	v_exp_f32_e32 v217, v61
	v_exp_f32_e32 v219, v62
	s_waitcnt lgkmcnt(7)
	v_mfma_f32_32x32x16_bf16 v[96:111], v[112:115], v[138:141], v[96:111]
	s_waitcnt lgkmcnt(6)
	v_mfma_f32_32x32x16_bf16 v[96:111], v[194:197], v[150:153], v[96:111]
	v_exp_f32_e32 v221, v63
	v_exp_f32_e32 v226, v68
	v_exp_f32_e32 v228, v69
	v_exp_f32_e32 v223, v74
	v_exp_f32_e32 v225, v75
	v_exp_f32_e32 v227, v76
	v_exp_f32_e32 v229, v77
	v_mfma_f32_32x32x16_bf16 v[112:127], v[178:181], v[130:133], v[32:47]
	v_exp_f32_e32 v178, v64
	v_exp_f32_e32 v180, v65
	v_cvt_pk_bf16_f32 v64, v206, v208
	v_cvt_pk_bf16_f32 v65, v210, v212
	v_exp_f32_e32 v179, v72
	v_exp_f32_e32 v181, v73
	ds_read_b64_tr_b16 v[56:57], v175 offset:21504
	ds_read_b64_tr_b16 v[58:59], v175 offset:23040
	ds_read_b64_tr_b16 v[62:63], v175 offset:23104
	ds_read_b64_tr_b16 v[60:61], v175 offset:21568
	v_mfma_f32_32x32x16_bf16 v[112:127], v[182:185], v[134:137], v[112:127]
	v_exp_f32_e32 v182, v70
	v_exp_f32_e32 v184, v71
	v_exp_f32_e32 v183, v78
	v_exp_f32_e32 v185, v79
	v_pk_add_f32 v[194:195], v[206:207], v[208:209]
	v_pk_add_f32 v[196:197], v[210:211], v[212:213]
	v_cvt_pk_bf16_f32 v68, v207, v209
	s_waitcnt lgkmcnt(9)
	v_mfma_f32_32x32x16_bf16 v[112:127], v[198:201], v[138:141], v[112:127]
	v_cvt_pk_bf16_f32 v69, v211, v213
	v_cvt_pk_bf16_f32 v70, v215, v217
	v_cvt_pk_bf16_f32 v71, v219, v221
	v_cvt_pk_bf16_f32 v72, v178, v180
	v_cvt_pk_bf16_f32 v76, v179, v181
	v_pk_add_f32 v[178:179], v[178:179], v[180:181]
	v_cvt_pk_bf16_f32 v73, v222, v224
	s_waitcnt lgkmcnt(6)
	v_mfma_f32_32x32x16_bf16 v[16:31], v[48:51], v[64:67], v[16:31]
	v_add_f32_e64 v48, v194, v196
	v_add_f32_e64 v49, v195, v197
	v_add_f32_e64 v50, v214, v216
	v_add_f32_e64 v51, v215, v217
	v_add_f32_e64 v194, v218, v220
	v_add_f32_e64 v195, v219, v221
	v_pk_add_f32 v[50:51], v[50:51], v[194:195]
	v_cvt_pk_bf16_f32 v74, v226, v228
	s_waitcnt lgkmcnt(4)
	v_mfma_f32_32x32x16_bf16 v[0:15], v[52:55], v[64:67], v[0:15]
	v_add_f32_e64 v52, v222, v224
	v_add_f32_e64 v53, v223, v225
	v_add_f32_e64 v54, v226, v228
	v_add_f32_e64 v55, v227, v229
	v_add_f32_e64 v64, v182, v184
	v_add_f32_e64 v65, v183, v185
	v_pk_add_f32 v[52:53], v[178:179], v[52:53]
	v_pk_add_f32 v[54:55], v[54:55], v[64:65]
	v_pk_add_f32 v[48:49], v[48:49], v[52:53]
	v_pk_add_f32 v[50:51], v[50:51], v[54:55]
	v_mfma_f32_32x32x16_bf16 v[112:127], v[202:205], v[150:153], v[112:127]
	v_add_f32_e64 v48, v48, v50
	v_add_f32_e64 v49, v49, v51
	v_max3_f32 v52, v96, v97, v98
	v_max_f32_e32 v53, v99, v100
	v_add_f32_e32 v64, v48, v49
	ds_read_b64_tr_b16 v[48:49], v175 offset:24576
	ds_read_b64_tr_b16 v[50:51], v175 offset:26112
	s_waitcnt lgkmcnt(4)
	v_mfma_f32_32x32x16_bf16 v[16:31], v[56:59], v[68:71], v[16:31]
	v_max3_f32 v58, v52, v102, v103
	v_max3_f32 v59, v53, v101, v104
	ds_read_b64_tr_b16 v[54:55], v175 offset:26176
	ds_read_b64_tr_b16 v[52:53], v175 offset:24640
	v_cvt_pk_bf16_f32 v75, v182, v184
	v_max3_f32 v56, v112, v113, v114
	v_max3_f32 v57, v115, v116, v117
	v_cvt_pk_bf16_f32 v77, v223, v225
	s_waitcnt lgkmcnt(4)
	v_mfma_f32_32x32x16_bf16 v[0:15], v[60:63], v[68:71], v[0:15]
	v_cvt_pk_bf16_f32 v78, v227, v229
	v_cvt_pk_bf16_f32 v79, v183, v185
	s_waitcnt lgkmcnt(2)
	v_mfma_f32_32x32x16_bf16 v[16:31], v[48:51], v[72:75], v[16:31]
	v_max3_f32 v48, v56, v118, v119
	v_max3_f32 v49, v57, v120, v121
	v_max3_f32 v50, v58, v106, v107
	v_max3_f32 v51, v59, v105, v108
	v_max3_f32 v48, v48, v122, v123
	v_max3_f32 v49, v49, v124, v125
	v_max3_f32 v50, v50, v110, v111
	s_waitcnt lgkmcnt(0)
	v_mfma_f32_32x32x16_bf16 v[0:15], v[52:55], v[72:75], v[0:15]
	v_max3_f32 v48, v48, v126, v127
	v_max3_f32 v49, v51, v109, v49
	ds_read_b64_tr_b16 v[56:57], v175 offset:27648
	ds_read_b64_tr_b16 v[58:59], v175 offset:29184
	v_max3_f32 v48, v50, v48, v49
	ds_read_b64_tr_b16 v[52:53], v175 offset:29248
	ds_read_b64_tr_b16 v[50:51], v175 offset:27712
	v_mov_b32_e32 v49, v48
	v_cndmask_b32_e64 v54, 0, 1, s[2:3]
	s_waitcnt lgkmcnt(2)
	v_mfma_f32_32x32x16_bf16 v[16:31], v[56:59], v[76:79], v[16:31]
	v_permlane32_swap_b32_e32 v48, v49
	v_add_f32_e32 v176, v176, v64
	v_cmp_ne_u32_e64 s[4:5], 1, v54
	s_waitcnt lgkmcnt(0)
	v_mfma_f32_32x32x16_bf16 v[0:15], v[50:53], v[76:79], v[0:15]
	s_andn2_b64 vcc, exec, s[2:3]
	s_cbranch_vccnz .LBB0_519
	v_max_f32_e32 v48, v48, v49
	v_cmp_lt_f32_e32 vcc, s45, v48
	s_cbranch_vccnz .LBB0_533

.LBB0_523:
	s_cmp_lt_u32 s1, s0
	s_cselect_b64 s[4:5], -1, 0
	s_cmp_ge_u32 s1, s0
	s_waitcnt lgkmcnt(0)
	s_cbranch_scc1 .LBB0_525
	v_add_co_u32_e32 v48, vcc, 0x6e10000, v160
	s_nop 1
	v_addc_co_u32_e32 v49, vcc, 0, v161, vcc
	global_load_dwordx4 v[142:145], v[48:49], off offset:1856

.LBB0_527:
	s_barrier
	ds_read_b128 v[64:67], v165
	ds_read_b128 v[68:71], v165 offset:32
	ds_read_b128 v[72:75], v165 offset:4608
	ds_read_b128 v[76:79], v165 offset:4640
	v_exp_f32_e32 v194, v96
	s_waitcnt lgkmcnt(3)
	v_mfma_f32_32x32x16_bf16 v[48:63], v[64:67], v[130:133], v[32:47]
	ds_read_b128 v[64:67], v165 offset:64
	ds_read_b128 v[160:163], v165 offset:96
	ds_read_b128 v[178:181], v165 offset:4672
	ds_read_b128 v[182:185], v165 offset:4704
	v_exp_f32_e32 v196, v97
	v_exp_f32_e32 v198, v98
	v_exp_f32_e32 v200, v99
	v_exp_f32_e32 v202, v100
	v_exp_f32_e32 v204, v101
	v_exp_f32_e32 v206, v102
	s_waitcnt lgkmcnt(5)
	v_mfma_f32_32x32x16_bf16 v[80:95], v[72:75], v[130:133], v[32:47]
	v_exp_f32_e32 v208, v103
	v_exp_f32_e32 v195, v104
	v_exp_f32_e32 v197, v105
	v_exp_f32_e32 v199, v106
	v_exp_f32_e32 v201, v107
	v_exp_f32_e32 v203, v108
	v_exp_f32_e32 v205, v109
	s_waitcnt lgkmcnt(4)
	v_mfma_f32_32x32x16_bf16 v[80:95], v[76:79], v[134:137], v[80:95]
	v_exp_f32_e32 v207, v110
	v_exp_f32_e32 v209, v111
	ds_read_b64_tr_b16 v[96:97], v175 offset:30720
	ds_read_b64_tr_b16 v[98:99], v175 offset:32256
	ds_read_b64_tr_b16 v[102:103], v175 offset:32320
	ds_read_b64_tr_b16 v[100:101], v175 offset:30784
	ds_read_b64_tr_b16 v[104:105], v175 offset:33792
	ds_read_b64_tr_b16 v[106:107], v175 offset:35328
	ds_read_b64_tr_b16 v[110:111], v175 offset:35392
	ds_read_b64_tr_b16 v[108:109], v175 offset:33856
	v_exp_f32_e32 v112, v112
	v_exp_f32_e32 v210, v113
	v_exp_f32_e32 v114, v114
	v_exp_f32_e32 v212, v115
	v_mfma_f32_32x32x16_bf16 v[48:63], v[68:71], v[134:137], v[48:63]
	v_exp_f32_e32 v113, v120
	v_exp_f32_e32 v211, v121
	v_exp_f32_e32 v115, v122
	v_exp_f32_e32 v213, v123
	v_exp_f32_e32 v116, v116
	v_exp_f32_e32 v214, v117
	v_exp_f32_e32 v118, v118
	s_waitcnt lgkmcnt(8)
	v_mfma_f32_32x32x16_bf16 v[80:95], v[178:181], v[138:141], v[80:95]
	v_mfma_f32_32x32x16_bf16 v[48:63], v[64:67], v[138:141], v[48:63]
	v_mfma_f32_32x32x16_bf16 v[64:79], v[182:185], v[150:153], v[80:95]
	v_mfma_f32_32x32x16_bf16 v[48:63], v[160:163], v[150:153], v[48:63]
	v_exp_f32_e32 v216, v119
	v_exp_f32_e32 v117, v124
	v_exp_f32_e32 v215, v125
	v_exp_f32_e32 v119, v126
	v_exp_f32_e32 v217, v127
	v_pk_add_f32 v[120:121], v[206:207], v[208:209]
	s_and_b64 vcc, exec, s[2:3]
	s_nop 1
	v_cvt_pk_bf16_f32 v80, v194, v196
	v_cvt_pk_bf16_f32 v81, v198, v200
	v_cvt_pk_bf16_f32 v82, v202, v204
	v_cvt_pk_bf16_f32 v83, v206, v208
	v_cvt_pk_bf16_f32 v84, v195, v197
	v_cvt_pk_bf16_f32 v85, v199, v201
	v_cvt_pk_bf16_f32 v86, v203, v205
	v_cvt_pk_bf16_f32 v87, v207, v209
	v_cvt_pk_bf16_f32 v88, v112, v210
	v_cvt_pk_bf16_f32 v89, v114, v212
	v_cvt_pk_bf16_f32 v90, v116, v214
	s_waitcnt lgkmcnt(6)
	v_mfma_f32_32x32x16_bf16 v[16:31], v[96:99], v[80:83], v[16:31]
	v_add_f32_e64 v96, v194, v196
	v_add_f32_e64 v97, v195, v197
	v_add_f32_e64 v98, v198, v200
	v_add_f32_e64 v99, v199, v201
	v_cvt_pk_bf16_f32 v91, v118, v216
	v_pk_add_f32 v[96:97], v[96:97], v[98:99]
	v_pk_add_f32 v[98:99], v[202:203], v[204:205]
	v_pk_add_f32 v[98:99], v[98:99], v[120:121]
	s_waitcnt lgkmcnt(4)
	v_mfma_f32_32x32x16_bf16 v[0:15], v[100:103], v[80:83], v[0:15]
	v_add_f32_e64 v80, v98, 0
	v_add_f32_e64 v81, v99, 0
	v_add_f32_e64 v82, v112, v210
	v_add_f32_e64 v83, v113, v211
	v_add_f32_e64 v98, v114, v212
	v_add_f32_e64 v99, v115, v213
	v_pk_add_f32 v[100:101], v[118:119], v[216:217]
	v_pk_add_f32 v[82:83], v[82:83], v[98:99]
	v_pk_add_f32 v[98:99], v[116:117], v[214:215]
	v_pk_add_f32 v[82:83], v[82:83], v[96:97]
	v_add_f32_e64 v98, v98, v100
	v_add_f32_e64 v99, v99, v101
	v_max3_f32 v97, v48, v49, v50
	v_add_f32_e64 v80, v98, v80
	v_add_f32_e64 v81, v99, v81
	v_cvt_pk_bf16_f32 v92, v113, v211
	v_pk_add_f32 v[80:81], v[82:83], v[80:81]
	v_cvt_pk_bf16_f32 v93, v115, v213
	v_add_f32_e32 v96, v80, v81
	s_waitcnt lgkmcnt(2)
	v_mfma_f32_32x32x16_bf16 v[16:31], v[104:107], v[84:87], v[16:31]
	ds_read_b64_tr_b16 v[80:81], v175 offset:36864
	ds_read_b64_tr_b16 v[82:83], v175 offset:38400
	v_max3_f32 v99, v64, v65, v66
	v_max3_f32 v100, v67, v68, v69
	v_cvt_pk_bf16_f32 v94, v117, v215
	v_cvt_pk_bf16_f32 v95, v119, v217
	v_add_f32_e32 v176, v176, v96
	s_waitcnt lgkmcnt(2)
	v_mfma_f32_32x32x16_bf16 v[0:15], v[108:111], v[84:87], v[0:15]
	v_max_f32_e32 v98, v51, v52
	ds_read_b64_tr_b16 v[86:87], v175 offset:38464
	ds_read_b64_tr_b16 v[84:85], v175 offset:36928
	s_waitcnt lgkmcnt(2)
	v_mfma_f32_32x32x16_bf16 v[16:31], v[80:83], v[88:91], v[16:31]
	v_max3_f32 v80, v97, v54, v55
	v_max3_f32 v97, v98, v53, v56
	v_max3_f32 v98, v99, v70, v71
	v_max3_f32 v99, v100, v72, v73
	v_max3_f32 v100, v80, v58, v59
	ds_read_b64_tr_b16 v[80:81], v175 offset:39936
	ds_read_b64_tr_b16 v[82:83], v175 offset:41472
	s_waitcnt lgkmcnt(2)
	v_mfma_f32_32x32x16_bf16 v[0:15], v[84:87], v[88:91], v[0:15]
	v_max3_f32 v84, v98, v74, v75
	v_max3_f32 v91, v84, v78, v79
	ds_read_b64_tr_b16 v[86:87], v175 offset:41536
	ds_read_b64_tr_b16 v[84:85], v175 offset:40000
	v_max3_f32 v88, v97, v57, v60
	v_max3_f32 v89, v99, v76, v77
	v_max3_f32 v90, v100, v62, v63
	s_waitcnt lgkmcnt(2)
	v_mfma_f32_32x32x16_bf16 v[16:31], v[80:83], v[92:95], v[16:31]
	v_max3_f32 v80, v88, v61, v89
	v_max3_f32 v80, v90, v91, v80
	v_mov_b32_e32 v81, v80
	s_nop 1
	v_permlane32_swap_b32_e32 v80, v81
	s_waitcnt lgkmcnt(0)
	v_mfma_f32_32x32x16_bf16 v[0:15], v[84:87], v[92:95], v[0:15]
	s_cbranch_vccnz .LBB0_529
	v_max_f32_e32 v80, v80, v81
	v_cmp_lt_f32_e32 vcc, s45, v80
	s_cbranch_vccnz .LBB0_534

.LBB0_602:
	v_bfe_u32 v0, v24, 2, 2
	v_lshl_or_b32 v0, v25, 2, v0
	v_mad_u32_u24 v4, v0, s43, 0
	v_and_b32_e32 v0, 16, v24
	v_lshlrev_b32_e32 v1, 2, v24
	s_and_b64 s[6:7], s[6:7], exec
	v_and_or_b32 v0, v1, 12, v0
	v_lshlrev_b64 v[2:3], 12, v[174:175]
	s_cselect_b32 s13, 4, 0x44
	v_lshlrev_b32_e32 v5, 1, v0
	v_subrev_u32_e32 v0, 64, v36
	v_mov_b32_e32 v1, v129
	v_lshl_add_u64 v[2:3], s[92:93], 0, v[2:3]
	s_add_u32 s0, s1, s0
	v_mov_b32_e32 v31, v129
	v_lshl_add_u64 v[178:179], v[0:1], 1, v[2:3]
	v_lshl_add_u64 v[0:1], s[92:93], 0, v[28:29]
	s_addc_u32 s1, 0, 0
	v_ashrrev_i32_e32 v37, 31, v36
	v_lshl_add_u64 v[180:181], v[30:31], 1, v[0:1]
	v_lshl_add_u64 v[0:1], s[0:1], 0, v[38:39]
	v_lshl_add_u64 v[130:131], v[26:27], 1, s[8:9]
	v_cmp_gt_i32_e64 s[6:7], 8, v34
	s_mov_b32 s33, 3
	v_lshl_add_u64 v[176:177], v[36:37], 1, s[8:9]
	v_add_u32_e32 v204, 0, v33
	v_lshl_add_u64 v[182:183], v[0:1], 0, v[128:129]
	v_add_u32_e32 v175, v4, v5
	v_mov_b32_e32 v33, v32
	v_mov_b32_e32 v34, v32
	v_mov_b32_e32 v35, v32
	v_mov_b32_e32 v36, v32
	v_mov_b32_e32 v37, v32
	v_mov_b32_e32 v38, v32
	v_mov_b32_e32 v39, v32
	v_mov_b32_e32 v40, v32
	v_mov_b32_e32 v41, v32
	v_mov_b32_e32 v42, v32
	v_mov_b32_e32 v43, v32
	v_mov_b32_e32 v44, v32
	v_mov_b32_e32 v45, v32
	v_mov_b32_e32 v46, v32
	v_mov_b32_e32 v47, v32
	v_mov_b32_e32 v16, v205
	v_mov_b32_e32 v17, v205
	v_mov_b32_e32 v18, v205
	v_mov_b32_e32 v19, v205
	v_mov_b32_e32 v20, v205
	v_mov_b32_e32 v21, v205
	v_mov_b32_e32 v22, v205
	v_mov_b32_e32 v23, v205
	v_mov_b32_e32 v24, v205
	v_mov_b32_e32 v25, v205
	v_mov_b32_e32 v26, v205
	v_mov_b32_e32 v27, v205
	v_mov_b32_e32 v28, v205
	v_mov_b32_e32 v29, v205
	v_mov_b32_e32 v30, v205
	v_mov_b32_e32 v31, v205
	v_mov_b32_e32 v0, v205
	v_mov_b32_e32 v1, v205
	v_mov_b32_e32 v2, v205
	v_mov_b32_e32 v3, v205
	v_mov_b32_e32 v4, v205
	v_mov_b32_e32 v5, v205
	v_mov_b32_e32 v6, v205
	v_mov_b32_e32 v7, v205
	v_mov_b32_e32 v8, v205
	v_mov_b32_e32 v9, v205
	v_mov_b32_e32 v10, v205
	v_mov_b32_e32 v11, v205
	v_mov_b32_e32 v12, v205
	v_mov_b32_e32 v13, v205
	v_mov_b32_e32 v14, v205
	v_mov_b32_e32 v15, v205
	s_add_i32 s0, s40, 2
	s_lshl_b32 s0, s0, 6
	v_add_u32_e32 v82, s0, v172
	v_mad_i64_i32 v[82:83], s[10:11], v82, s49, v[130:131]
	v_lshl_add_u64 v[82:83], v[82:83], 0, s[96:97]
	v_lshl_add_u64 v[80:81], s[74:75], 0, v[180:181]
	v_lshl_add_u64 v[80:81], v[80:81], 0, s[34:35]
	v_cndmask_b32_e64 v130, v80, v82, s[2:3]
	v_cndmask_b32_e64 v131, v81, v83, s[2:3]
	v_mov_b32_e32 v180, 0x40000
	v_mov_b32_e32 v80, 0x38000
	v_cndmask_b32_e64 v180, v180, v80, s[2:3]
	v_add_u32_e32 v82, s0, v174
	v_mad_i64_i32 v[82:83], s[10:11], v82, s49, v[176:177]
	v_lshl_add_u64 v[82:83], v[82:83], 0, s[96:97]
	v_lshl_add_u64 v[80:81], s[74:75], 0, v[178:179]
	v_lshl_add_u64 v[80:81], v[80:81], 0, s[34:35]
	v_cndmask_b32_e64 v176, v80, v82, s[6:7]
	v_cndmask_b32_e64 v177, v81, v83, s[6:7]
	v_mov_b32_e32 v178, 0x40000
	v_mov_b32_e32 v80, 0x38000
	v_cndmask_b32_e64 v178, v178, v80, s[6:7]
.LBB0_603:
	s_add_i32 s44, s40, 2
	s_add_i32 s85, s33, -1
	s_cmp_lt_u32 s85, s13
	s_cselect_b64 s[38:39], -1, 0
	s_cmp_ge_u32 s85, s13
	s_cbranch_scc1 .LBB0_615
	global_load_dwordx4 v[132:135], v[130:131], off
	v_add_co_u32_e32 v130, vcc, v180, v130
	s_nop 1
	v_addc_co_u32_e32 v131, vcc, 0, v131, vcc
	s_and_saveexec_b64 s[8:9], s[4:5]
	s_cbranch_execz .Lm0a_s1
	global_load_dwordx4 v[140:143], v[176:177], off
	v_add_co_u32_e32 v176, vcc, v178, v176
	s_nop 1
	v_addc_co_u32_e32 v177, vcc, 0, v177, vcc

.LBB0_617:
	s_barrier
	ds_read_b128 v[80:83], v202 offset:13312
	ds_read_b128 v[84:87], v202 offset:13344
	s_waitcnt lgkmcnt(1)
	v_mfma_f32_32x32x16_bf16 v[96:111], v[80:83], v[144:147], v[32:47]
	ds_read_b128 v[80:83], v202 offset:19968
	ds_read_b128 v[206:209], v202 offset:20000
	v_exp_f32_e32 v218, v48
	s_waitcnt lgkmcnt(2)
	v_mfma_f32_32x32x16_bf16 v[96:111], v[84:87], v[148:151], v[96:111]
	v_exp_f32_e32 v220, v49
	v_exp_f32_e32 v222, v50
	v_exp_f32_e32 v224, v51
	v_exp_f32_e32 v226, v52
	v_exp_f32_e32 v228, v53
	v_exp_f32_e32 v230, v54
	v_exp_f32_e32 v232, v55
	s_waitcnt lgkmcnt(1)
	v_mfma_f32_32x32x16_bf16 v[112:127], v[80:83], v[144:147], v[32:47]
	ds_read_b128 v[80:83], v202 offset:13376
	ds_read_b128 v[210:213], v202 offset:13408
	ds_read_b128 v[214:217], v202 offset:20032
	ds_read_b128 v[48:51], v202 offset:20064
	v_exp_f32_e32 v219, v56
	v_exp_f32_e32 v221, v57
	v_exp_f32_e32 v223, v58
	v_exp_f32_e32 v225, v59
	s_waitcnt lgkmcnt(4)
	v_mfma_f32_32x32x16_bf16 v[112:127], v[206:209], v[148:151], v[112:127]
	ds_read_b128 v[52:55], v202 offset:13440
	ds_read_b128 v[56:59], v202 offset:13472
	v_exp_f32_e32 v227, v60
	v_exp_f32_e32 v229, v61
	v_exp_f32_e32 v231, v62
	v_exp_f32_e32 v233, v63
	ds_read_b128 v[60:63], v202 offset:20096
	ds_read_b128 v[206:209], v202 offset:20128
	v_exp_f32_e32 v234, v68
	s_waitcnt lgkmcnt(7)
	v_mfma_f32_32x32x16_bf16 v[96:111], v[80:83], v[152:155], v[96:111]
	v_exp_f32_e32 v236, v69
	v_exp_f32_e32 v238, v70
	v_exp_f32_e32 v240, v71
	v_cvt_pk_bf16_f32 v68, v218, v220
	v_cvt_pk_bf16_f32 v69, v222, v224
	v_cvt_pk_bf16_f32 v70, v226, v228
	v_cvt_pk_bf16_f32 v71, v230, v232
	s_waitcnt lgkmcnt(5)
	v_mfma_f32_32x32x16_bf16 v[112:127], v[214:217], v[152:155], v[112:127]
	v_exp_f32_e32 v214, v66
	v_exp_f32_e32 v216, v67
	v_exp_f32_e32 v215, v74
	v_exp_f32_e32 v217, v75
	v_exp_f32_e32 v235, v76
	v_exp_f32_e32 v237, v77
	v_exp_f32_e32 v239, v78
	v_mfma_f32_32x32x16_bf16 v[96:111], v[210:213], v[156:159], v[96:111]
	v_exp_f32_e32 v210, v64
	v_exp_f32_e32 v212, v65
	v_exp_f32_e32 v211, v72
	v_exp_f32_e32 v213, v73
	v_exp_f32_e32 v241, v79
	v_cvt_pk_bf16_f32 v72, v210, v212
	v_cvt_pk_bf16_f32 v73, v214, v216
	s_waitcnt lgkmcnt(4)
	v_mfma_f32_32x32x16_bf16 v[112:127], v[48:51], v[156:159], v[112:127]
	v_cvt_pk_bf16_f32 v74, v234, v236
	v_cvt_pk_bf16_f32 v75, v238, v240
	v_cvt_pk_bf16_f32 v76, v211, v213
	v_cvt_pk_bf16_f32 v77, v215, v217
	v_cvt_pk_bf16_f32 v78, v235, v237
	v_cvt_pk_bf16_f32 v79, v239, v241
	s_waitcnt lgkmcnt(3)
	v_mfma_f32_32x32x16_bf16 v[96:111], v[52:55], v[160:163], v[96:111]
	ds_read_b64_tr_b16 v[48:49], v175 offset:26624
	ds_read_b64_tr_b16 v[50:51], v175 offset:28160
	ds_read_b64_tr_b16 v[54:55], v175 offset:28224
	ds_read_b64_tr_b16 v[52:53], v175 offset:26688
	s_waitcnt lgkmcnt(5)
	v_mfma_f32_32x32x16_bf16 v[112:127], v[60:63], v[160:163], v[112:127]
	ds_read_b64_tr_b16 v[60:61], v175 offset:29696
	ds_read_b64_tr_b16 v[62:63], v175 offset:31232
	ds_read_b64_tr_b16 v[66:67], v175 offset:31296
	ds_read_b64_tr_b16 v[64:65], v175 offset:29760
	s_andn2_b64 vcc, exec, s[8:9]
	s_waitcnt lgkmcnt(6)
	v_mfma_f32_32x32x16_bf16 v[16:31], v[48:51], v[68:71], v[16:31]
	v_add_f32_e64 v50, v226, v228
	v_add_f32_e64 v51, v227, v229
	s_waitcnt lgkmcnt(4)
	v_mfma_f32_32x32x16_bf16 v[0:15], v[52:55], v[68:71], v[0:15]
	v_add_f32_e64 v52, v214, v216
	v_add_f32_e64 v53, v215, v217
	v_add_f32_e64 v54, v234, v236
	v_add_f32_e64 v55, v235, v237
	v_add_f32_e64 v68, v238, v240
	v_add_f32_e64 v69, v239, v241
	v_pk_add_f32 v[54:55], v[54:55], v[68:69]
	v_mfma_f32_32x32x16_bf16 v[96:111], v[56:59], v[164:167], v[96:111]
	v_cvt_pk_bf16_f32 v56, v219, v221
	v_cvt_pk_bf16_f32 v57, v223, v225
	v_cvt_pk_bf16_f32 v58, v227, v229
	v_cvt_pk_bf16_f32 v59, v231, v233
	v_mfma_f32_32x32x16_bf16 v[112:127], v[206:209], v[164:167], v[112:127]
	v_add_f32_e64 v206, v218, v220
	v_add_f32_e64 v207, v219, v221
	v_add_f32_e64 v208, v222, v224
	v_add_f32_e64 v209, v223, v225
	v_add_f32_e64 v48, v206, v208
	v_add_f32_e64 v49, v207, v209
	v_pk_add_f32 v[206:207], v[230:231], v[232:233]
	v_pk_add_f32 v[50:51], v[50:51], v[206:207]
	v_pk_add_f32 v[206:207], v[210:211], v[212:213]
	v_pk_add_f32 v[52:53], v[206:207], v[52:53]
	s_waitcnt lgkmcnt(2)
	v_mfma_f32_32x32x16_bf16 v[16:31], v[60:63], v[56:59], v[16:31]
	v_add_f32_e64 v48, v48, v52
	v_add_f32_e64 v49, v49, v53
	v_add_f32_e64 v50, v50, v54
	v_add_f32_e64 v51, v51, v55
	v_pk_add_f32 v[48:49], v[48:49], v[50:51]
	v_max3_f32 v52, v96, v97, v98
	v_max_f32_e32 v53, v99, v100
	s_waitcnt lgkmcnt(0)
	v_mfma_f32_32x32x16_bf16 v[0:15], v[64:67], v[56:59], v[0:15]
	v_add_f32_e32 v60, v48, v49
	ds_read_b64_tr_b16 v[48:49], v175 offset:32768
	ds_read_b64_tr_b16 v[50:51], v175 offset:34304
	v_max3_f32 v58, v52, v102, v103
	v_max3_f32 v59, v53, v101, v104
	ds_read_b64_tr_b16 v[54:55], v175 offset:34368
	ds_read_b64_tr_b16 v[52:53], v175 offset:32832
	v_max3_f32 v56, v112, v113, v114
	v_max3_f32 v57, v115, v116, v117
	s_waitcnt lgkmcnt(2)
	v_mfma_f32_32x32x16_bf16 v[16:31], v[48:51], v[72:75], v[16:31]
	v_max3_f32 v48, v56, v118, v119
	v_max3_f32 v49, v57, v120, v121
	v_max3_f32 v50, v58, v106, v107
	v_max3_f32 v51, v59, v105, v108
	v_max3_f32 v48, v48, v122, v123
	v_max3_f32 v49, v49, v124, v125
	v_max3_f32 v50, v50, v110, v111
	s_waitcnt lgkmcnt(0)
	v_mfma_f32_32x32x16_bf16 v[0:15], v[52:55], v[72:75], v[0:15]
	v_max3_f32 v48, v48, v126, v127
	v_max3_f32 v49, v51, v109, v49
	ds_read_b64_tr_b16 v[56:57], v175 offset:35840
	ds_read_b64_tr_b16 v[58:59], v175 offset:37376
	v_max3_f32 v48, v50, v48, v49
	ds_read_b64_tr_b16 v[52:53], v175 offset:37440
	ds_read_b64_tr_b16 v[50:51], v175 offset:35904
	v_mov_b32_e32 v49, v48
	v_cndmask_b32_e64 v54, 0, 1, s[8:9]
	s_waitcnt lgkmcnt(2)
	v_mfma_f32_32x32x16_bf16 v[16:31], v[56:59], v[76:79], v[16:31]
	v_permlane32_swap_b32_e32 v48, v49
	v_add_f32_e32 v205, v205, v60
	v_cmp_ne_u32_e64 s[10:11], 1, v54
	s_waitcnt lgkmcnt(0)
	v_mfma_f32_32x32x16_bf16 v[0:15], v[50:53], v[76:79], v[0:15]
	s_cbranch_vccnz .LBB0_619
	v_max_f32_e32 v48, v48, v49
	v_cmp_lt_f32_e32 vcc, s45, v48
	s_cbranch_vccnz .LBB0_649

.LBB0_625:
	s_cmp_lt_u32 s33, s13
	s_cselect_b64 s[10:11], -1, 0
	s_cmp_ge_u32 s33, s13
	s_waitcnt lgkmcnt(0)
	s_cbranch_scc1 .LBB0_637
	global_load_dwordx4 v[132:135], v[130:131], off
	v_add_co_u32_e32 v130, vcc, v180, v130
	s_nop 1
	v_addc_co_u32_e32 v131, vcc, 0, v131, vcc
	s_and_saveexec_b64 s[38:39], s[4:5]
	s_cbranch_execz .Lm0a_s2
	global_load_dwordx4 v[140:143], v[176:177], off
	v_add_co_u32_e32 v176, vcc, v178, v176
	s_nop 1
	v_addc_co_u32_e32 v177, vcc, 0, v177, vcc

.LBB0_639:
	s_barrier
	ds_read_b128 v[64:67], v202
	ds_read_b128 v[68:71], v202 offset:32
	v_exp_f32_e32 v184, v96
	v_exp_f32_e32 v206, v97
	v_exp_f32_e32 v208, v98
	s_waitcnt lgkmcnt(1)
	v_mfma_f32_32x32x16_bf16 v[48:63], v[64:67], v[144:147], v[32:47]
	v_exp_f32_e32 v210, v99
	v_exp_f32_e32 v212, v100
	v_exp_f32_e32 v214, v101
	v_exp_f32_e32 v216, v102
	v_exp_f32_e32 v218, v103
	v_exp_f32_e32 v185, v104
	v_exp_f32_e32 v207, v105
	s_waitcnt lgkmcnt(0)
	v_mfma_f32_32x32x16_bf16 v[48:63], v[68:71], v[148:151], v[48:63]
	ds_read_b128 v[64:67], v202 offset:6656
	ds_read_b128 v[68:71], v202 offset:6688
	v_exp_f32_e32 v209, v106
	v_exp_f32_e32 v211, v107
	v_exp_f32_e32 v213, v108
	v_exp_f32_e32 v215, v109
	v_exp_f32_e32 v217, v110
	v_exp_f32_e32 v219, v111
	s_waitcnt lgkmcnt(1)
	v_mfma_f32_32x32x16_bf16 v[80:95], v[64:67], v[144:147], v[32:47]
	ds_read_b128 v[64:67], v202 offset:64
	ds_read_b128 v[72:75], v202 offset:96
	v_exp_f32_e32 v220, v112
	v_exp_f32_e32 v222, v113
	v_exp_f32_e32 v224, v114
	v_exp_f32_e32 v226, v115
	v_exp_f32_e32 v228, v116
	v_exp_f32_e32 v230, v117
	s_waitcnt lgkmcnt(1)
	v_mfma_f32_32x32x16_bf16 v[48:63], v[64:67], v[152:155], v[48:63]
	ds_read_b128 v[64:67], v202 offset:6720
	v_exp_f32_e32 v232, v118
	v_exp_f32_e32 v234, v119
	v_exp_f32_e32 v221, v120
	v_exp_f32_e32 v223, v121
	v_exp_f32_e32 v225, v122
	v_exp_f32_e32 v227, v123
	v_mfma_f32_32x32x16_bf16 v[80:95], v[68:71], v[148:151], v[80:95]
	ds_read_b128 v[68:71], v202 offset:6752
	v_exp_f32_e32 v229, v124
	v_exp_f32_e32 v231, v125
	v_exp_f32_e32 v233, v126
	v_exp_f32_e32 v235, v127
	s_and_b64 vcc, exec, s[8:9]
	s_waitcnt lgkmcnt(1)
	v_mfma_f32_32x32x16_bf16 v[80:95], v[64:67], v[152:155], v[80:95]
	s_waitcnt lgkmcnt(0)
	v_mfma_f32_32x32x16_bf16 v[80:95], v[68:71], v[156:159], v[80:95]
	v_mfma_f32_32x32x16_bf16 v[48:63], v[72:75], v[156:159], v[48:63]
	ds_read_b128 v[64:67], v202 offset:128
	ds_read_b128 v[96:99], v202 offset:160
	ds_read_b128 v[72:75], v202 offset:6784
	ds_read_b128 v[100:103], v202 offset:6816
	ds_read_b64_tr_b16 v[104:105], v175 offset:38912
	ds_read_b64_tr_b16 v[106:107], v175 offset:40448
	ds_read_b64_tr_b16 v[110:111], v175 offset:40512
	ds_read_b64_tr_b16 v[108:109], v175 offset:38976
	ds_read_b64_tr_b16 v[112:113], v175 offset:41984
	ds_read_b64_tr_b16 v[114:115], v175 offset:43520
	ds_read_b64_tr_b16 v[118:119], v175 offset:43584
	ds_read_b64_tr_b16 v[116:117], v175 offset:42048
	s_waitcnt lgkmcnt(8)
	v_mfma_f32_32x32x16_bf16 v[80:95], v[72:75], v[160:163], v[80:95]
	v_mfma_f32_32x32x16_bf16 v[48:63], v[64:67], v[160:163], v[48:63]
	v_mfma_f32_32x32x16_bf16 v[64:79], v[100:103], v[164:167], v[80:95]
	v_mfma_f32_32x32x16_bf16 v[48:63], v[96:99], v[164:167], v[48:63]
	v_add_f32_e64 v96, v184, v206
	v_add_f32_e64 v97, v185, v207
	v_add_f32_e64 v98, v208, v210
	v_add_f32_e64 v99, v209, v211
	v_pk_add_f32 v[96:97], v[96:97], v[98:99]
	v_pk_add_f32 v[98:99], v[212:213], v[214:215]
	s_nop 2
	v_cvt_pk_bf16_f32 v80, v184, v206
	v_cvt_pk_bf16_f32 v81, v208, v210
	v_cvt_pk_bf16_f32 v82, v212, v214
	v_cvt_pk_bf16_f32 v83, v216, v218
	v_cvt_pk_bf16_f32 v84, v185, v207
	v_cvt_pk_bf16_f32 v85, v209, v211
	v_cvt_pk_bf16_f32 v86, v213, v215
	s_waitcnt lgkmcnt(6)
	v_mfma_f32_32x32x16_bf16 v[16:31], v[104:107], v[80:83], v[16:31]
	v_cvt_pk_bf16_f32 v87, v217, v219
	v_add_f32_e64 v96, v96, 0
	v_add_f32_e64 v97, v97, 0
	v_cvt_pk_bf16_f32 v88, v220, v222
	v_cvt_pk_bf16_f32 v89, v224, v226
	v_cvt_pk_bf16_f32 v90, v228, v230
	v_cvt_pk_bf16_f32 v91, v232, v234
	v_cvt_pk_bf16_f32 v92, v221, v223
	s_waitcnt lgkmcnt(4)
	v_mfma_f32_32x32x16_bf16 v[0:15], v[108:111], v[80:83], v[0:15]
	v_add_f32_e64 v82, v220, v222
	v_add_f32_e64 v83, v221, v223
	v_cvt_pk_bf16_f32 v93, v225, v227
	v_cvt_pk_bf16_f32 v94, v229, v231
	v_cvt_pk_bf16_f32 v95, v233, v235
	v_add_f32_e64 v100, v216, v218
	v_add_f32_e64 v101, v217, v219
	v_add_f32_e64 v98, v98, v100
	v_add_f32_e64 v99, v99, v101
	v_add_f32_e64 v100, v232, v234
	v_add_f32_e64 v101, v233, v235
	v_pk_add_f32 v[80:81], v[98:99], 0 op_sel_hi:[1,0]
	v_pk_add_f32 v[98:99], v[224:225], v[226:227]
	s_nop 0
	v_pk_add_f32 v[82:83], v[82:83], v[98:99]
	v_pk_add_f32 v[98:99], v[228:229], v[230:231]
	s_waitcnt lgkmcnt(2)
	v_mfma_f32_32x32x16_bf16 v[16:31], v[112:115], v[84:87], v[16:31]
	v_add_f32_e64 v98, v98, v100
	v_add_f32_e64 v99, v99, v101
	v_add_f32_e64 v82, v82, v96
	v_add_f32_e64 v83, v83, v97
	v_add_f32_e64 v80, v98, v80
	v_add_f32_e64 v81, v99, v81
	v_max3_f32 v97, v48, v49, v50
	v_pk_add_f32 v[80:81], v[82:83], v[80:81]
	v_max3_f32 v99, v64, v65, v66
	v_add_f32_e32 v96, v80, v81
	s_waitcnt lgkmcnt(0)
	v_mfma_f32_32x32x16_bf16 v[0:15], v[116:119], v[84:87], v[0:15]
	ds_read_b64_tr_b16 v[80:81], v175 offset:45056
	ds_read_b64_tr_b16 v[82:83], v175 offset:46592
	v_max_f32_e32 v98, v51, v52
	ds_read_b64_tr_b16 v[86:87], v175 offset:46656
	ds_read_b64_tr_b16 v[84:85], v175 offset:45120
	v_max3_f32 v100, v67, v68, v69
	v_add_f32_e32 v205, v205, v96
	s_waitcnt lgkmcnt(2)
	v_mfma_f32_32x32x16_bf16 v[16:31], v[80:83], v[88:91], v[16:31]
	v_max3_f32 v80, v97, v54, v55
	v_max3_f32 v97, v98, v53, v56
	v_max3_f32 v98, v99, v70, v71
	v_max3_f32 v99, v100, v72, v73
	v_max3_f32 v100, v80, v58, v59
	ds_read_b64_tr_b16 v[80:81], v175 offset:48128
	ds_read_b64_tr_b16 v[82:83], v175 offset:49664
	s_waitcnt lgkmcnt(2)
	v_mfma_f32_32x32x16_bf16 v[0:15], v[84:87], v[88:91], v[0:15]
	v_max3_f32 v84, v98, v74, v75
	v_max3_f32 v91, v84, v78, v79
	ds_read_b64_tr_b16 v[86:87], v175 offset:49728
	ds_read_b64_tr_b16 v[84:85], v175 offset:48192
	v_max3_f32 v88, v97, v57, v60
	v_max3_f32 v89, v99, v76, v77
	v_max3_f32 v90, v100, v62, v63
	s_waitcnt lgkmcnt(2)
	v_mfma_f32_32x32x16_bf16 v[16:31], v[80:83], v[92:95], v[16:31]
	v_max3_f32 v80, v88, v61, v89
	v_max3_f32 v80, v90, v91, v80
	v_mov_b32_e32 v81, v80
	s_nop 1
	v_permlane32_swap_b32_e32 v80, v81
	s_waitcnt lgkmcnt(0)
	v_mfma_f32_32x32x16_bf16 v[0:15], v[84:87], v[92:95], v[0:15]
	s_cbranch_vccnz .LBB0_641
	v_max_f32_e32 v80, v80, v81
	v_cmp_lt_f32_e32 vcc, s45, v80
	s_cbranch_vccnz .LBB0_650

.LBB0_647:
	s_add_i32 s33, s33, 2
	s_mov_b64 s[0:1], 0x70000
	s_cmp_lt_u32 s85, s13
	v_lshl_add_u64 v[182:183], v[182:183], 0, s[0:1]
	s_waitcnt lgkmcnt(0)
	s_cbranch_scc1 .Lrot0a_c
	s_barrier
	s_branch .LBB0_497
.Lrot0a_c:
	s_mov_b32 s40, s44
	s_branch .LBB0_603

.LBB0_1753:
	v_mul_u32_u24_e32 v174, 0x90, v8
	v_bfe_u32 v8, v6, 2, 2
	v_lshl_add_u64 v[0:1], s[14:15], 0, v[0:1]
	v_and_b32_e32 v173, 63, v6
	v_lshlrev_b32_e32 v172, 3, v7
	v_lshl_or_b32 v7, v7, 2, v8
	v_and_b32_e32 v8, 16, v6
	v_lshlrev_b32_e32 v6, 2, v6
	v_lshl_add_u64 v[0:1], v[2:3], 1, v[0:1]
	v_mul_u32_u24_e32 v7, 0xc0, v7
	v_and_or_b32 v6, v6, 12, v8
	v_lshl_add_u64 v[156:157], s[74:75], 0, v[0:1]
	v_lshl_add_u64 v[0:1], s[14:15], 0, v[4:5]
	v_lshlrev_b32_e32 v6, 1, v6
	v_add_u32_e32 v7, 0, v7
	v_lshl_add_u64 v[0:1], v[0:1], 0, v[128:129]
	s_lshl_b32 s45, s86, 6
	v_lshlrev_b32_e32 v170, 3, v9
	s_mov_b32 s9, s15
	v_lshl_add_u64 v[158:159], s[74:75], 0, v[0:1]
	v_add_u32_e32 v175, v7, v6
	v_mov_b32_e32 v33, v32
	v_mov_b32_e32 v34, v32
	v_mov_b32_e32 v35, v32
	v_mov_b32_e32 v36, v32
	v_mov_b32_e32 v37, v32
	v_mov_b32_e32 v38, v32
	v_mov_b32_e32 v39, v32
	v_mov_b32_e32 v40, v32
	v_mov_b32_e32 v41, v32
	v_mov_b32_e32 v42, v32
	v_mov_b32_e32 v43, v32
	v_mov_b32_e32 v44, v32
	v_mov_b32_e32 v45, v32
	v_mov_b32_e32 v46, v32
	v_mov_b32_e32 v47, v32
	v_mov_b32_e32 v16, v176
	v_mov_b32_e32 v17, v176
	v_mov_b32_e32 v18, v176
	v_mov_b32_e32 v19, v176
	v_mov_b32_e32 v20, v176
	v_mov_b32_e32 v21, v176
	v_mov_b32_e32 v22, v176
	v_mov_b32_e32 v23, v176
	v_mov_b32_e32 v24, v176
	v_mov_b32_e32 v25, v176
	v_mov_b32_e32 v26, v176
	v_mov_b32_e32 v27, v176
	v_mov_b32_e32 v28, v176
	v_mov_b32_e32 v29, v176
	v_mov_b32_e32 v30, v176
	v_mov_b32_e32 v31, v176
	v_mov_b32_e32 v0, v176
	v_mov_b32_e32 v1, v176
	v_mov_b32_e32 v2, v176
	v_mov_b32_e32 v3, v176
	v_mov_b32_e32 v4, v176
	v_mov_b32_e32 v5, v176
	v_mov_b32_e32 v6, v176
	v_mov_b32_e32 v7, v176
	v_mov_b32_e32 v8, v176
	v_mov_b32_e32 v9, v176
	v_mov_b32_e32 v10, v176
	v_mov_b32_e32 v11, v176
	v_mov_b32_e32 v12, v176
	v_mov_b32_e32 v13, v176
	v_mov_b32_e32 v14, v176
	v_mov_b32_e32 v15, v176
	s_branch .LBB0_1755
.LBB0_1754:
	s_add_i32 s44, s44, 2
	v_lshl_add_u64 v[156:157], v[156:157], 0, s[16:17]
	s_andn2_b64 vcc, exec, s[38:39]
	v_lshl_add_u64 v[158:159], v[158:159], 0, s[16:17]
	s_waitcnt lgkmcnt(0)
	s_cbranch_vccnz .Lrot1b_c
	s_barrier
	s_branch .LBB0_1772
.Lrot1b_c:
.LBB0_1755:
	s_cmpk_lt_u32 s44, 0x42
	s_cselect_b64 s[40:41], -1, 0
	s_cmpk_gt_u32 s44, 0x41
	s_cselect_b64 s[38:39], -1, 0
	s_and_b64 vcc, exec, s[38:39]
	v_lshl_add_u64 v[160:161], v[156:157], 0, s[8:9]
	s_cbranch_vccnz .LBB0_1757
	v_add_co_u32_e32 v80, vcc, 0x6dd0000, v160
	s_nop 1
	v_addc_co_u32_e32 v81, vcc, 0, v161, vcc
	global_load_dwordx4 v[146:149], v[80:81], off offset:1856
.LBB0_1757:
	s_barrier
	ds_read_b128 v[112:115], v165 offset:9216
	ds_read_b128 v[116:119], v165 offset:9248
	v_lshl_add_u64 v[162:163], v[158:159], 0, s[8:9]
	v_exp_f32_e32 v208, v48
	v_add_co_u32_e32 v48, vcc, 0x6d90000, v162
	v_exp_f32_e32 v210, v49
	s_nop 0
	v_addc_co_u32_e32 v49, vcc, 0, v163, vcc
	s_waitcnt lgkmcnt(1)
	v_mfma_f32_32x32x16_bf16 v[96:111], v[112:115], v[130:133], v[32:47]
	ds_read_b128 v[178:181], v165 offset:13824
	ds_read_b128 v[182:185], v165 offset:13856
	ds_read_b128 v[112:115], v165 offset:9280
	ds_read_b128 v[196:199], v165 offset:9312
	ds_read_b128 v[200:203], v165 offset:13888
	ds_read_b128 v[204:207], v165 offset:13920
	global_load_dwordx4 v[150:153], v[48:49], off offset:2112
	v_exp_f32_e32 v212, v50
	v_exp_f32_e32 v214, v51
	v_exp_f32_e32 v216, v52
	v_exp_f32_e32 v218, v53
	v_exp_f32_e32 v220, v54
	s_waitcnt lgkmcnt(6)
	v_mfma_f32_32x32x16_bf16 v[96:111], v[116:119], v[134:137], v[96:111]
	v_exp_f32_e32 v222, v55
	v_exp_f32_e32 v209, v56
	v_exp_f32_e32 v211, v57
	v_exp_f32_e32 v213, v58
	v_exp_f32_e32 v215, v59
	v_exp_f32_e32 v217, v60
	v_exp_f32_e32 v219, v61
	s_waitcnt lgkmcnt(3)
	v_mfma_f32_32x32x16_bf16 v[96:111], v[112:115], v[138:141], v[96:111]
	v_exp_f32_e32 v221, v62
	v_exp_f32_e32 v223, v63
	v_mfma_f32_32x32x16_bf16 v[112:127], v[178:181], v[130:133], v[32:47]
	v_exp_f32_e32 v178, v64
	v_exp_f32_e32 v180, v65
	ds_read_b64_tr_b16 v[48:49], v175 offset:18432
	ds_read_b64_tr_b16 v[50:51], v175 offset:19968
	ds_read_b64_tr_b16 v[54:55], v175 offset:20032
	ds_read_b64_tr_b16 v[52:53], v175 offset:18496
	ds_read_b64_tr_b16 v[56:57], v175 offset:21504
	ds_read_b64_tr_b16 v[58:59], v175 offset:23040
	ds_read_b64_tr_b16 v[62:63], v175 offset:23104
	ds_read_b64_tr_b16 v[60:61], v175 offset:21568
	v_cvt_pk_bf16_f32 v64, v208, v210
	v_cvt_pk_bf16_f32 v65, v212, v214
	v_exp_f32_e32 v179, v72
	v_exp_f32_e32 v181, v73
	v_mfma_f32_32x32x16_bf16 v[112:127], v[182:185], v[134:137], v[112:127]
	v_exp_f32_e32 v182, v66
	v_exp_f32_e32 v184, v67
	v_cvt_pk_bf16_f32 v66, v216, v218
	v_cvt_pk_bf16_f32 v67, v220, v222
	v_exp_f32_e32 v183, v74
	v_exp_f32_e32 v185, v75
	v_exp_f32_e32 v224, v68
	s_waitcnt lgkmcnt(6)
	v_mfma_f32_32x32x16_bf16 v[16:31], v[48:51], v[64:67], v[16:31]
	v_exp_f32_e32 v226, v69
	v_exp_f32_e32 v228, v70
	v_exp_f32_e32 v230, v71
	v_exp_f32_e32 v225, v76
	v_exp_f32_e32 v227, v77
	v_exp_f32_e32 v229, v78
	v_exp_f32_e32 v231, v79
	s_waitcnt lgkmcnt(4)
	v_mfma_f32_32x32x16_bf16 v[0:15], v[52:55], v[64:67], v[0:15]
	v_add_f32_e64 v48, v208, v210
	v_add_f32_e64 v49, v209, v211
	v_add_f32_e64 v50, v212, v214
	v_add_f32_e64 v51, v213, v215
	v_add_f32_e64 v52, v178, v180
	v_add_f32_e64 v53, v179, v181
	v_pk_add_f32 v[48:49], v[48:49], v[50:51]
	v_pk_add_f32 v[50:51], v[216:217], v[218:219]
	v_pk_add_f32 v[54:55], v[182:183], v[184:185]
	v_cvt_pk_bf16_f32 v68, v209, v211
	v_mfma_f32_32x32x16_bf16 v[112:127], v[200:203], v[138:141], v[112:127]
	v_cvt_pk_bf16_f32 v69, v213, v215
	v_cvt_pk_bf16_f32 v70, v217, v219
	v_cvt_pk_bf16_f32 v71, v221, v223
	v_add_f32_e64 v52, v52, v54
	v_add_f32_e64 v53, v53, v55
	v_pk_add_f32 v[54:55], v[224:225], v[226:227]
	v_pk_add_f32 v[64:65], v[228:229], v[230:231]
	v_mfma_f32_32x32x16_bf16 v[96:111], v[196:199], v[142:145], v[96:111]
	v_add_f32_e64 v196, v220, v222
	v_add_f32_e64 v197, v221, v223
	v_add_f32_e64 v54, v54, v64
	v_add_f32_e64 v55, v55, v65
	v_add_f32_e64 v50, v50, v196
	v_add_f32_e64 v51, v51, v197
	v_pk_add_f32 v[48:49], v[48:49], v[52:53]
	v_cvt_pk_bf16_f32 v72, v178, v180
	v_pk_add_f32 v[50:51], v[50:51], v[54:55]
	s_waitcnt lgkmcnt(2)
	v_mfma_f32_32x32x16_bf16 v[16:31], v[56:59], v[68:71], v[16:31]
	v_add_f32_e64 v48, v48, v50
	v_add_f32_e64 v49, v49, v51
	v_add_f32_e32 v56, v48, v49
	ds_read_b64_tr_b16 v[48:49], v175 offset:24576
	ds_read_b64_tr_b16 v[50:51], v175 offset:26112
	v_max_f32_e32 v58, v99, v100
	ds_read_b64_tr_b16 v[54:55], v175 offset:26176
	ds_read_b64_tr_b16 v[52:53], v175 offset:24640
	s_waitcnt lgkmcnt(4)
	v_mfma_f32_32x32x16_bf16 v[0:15], v[60:63], v[68:71], v[0:15]
	v_cvt_pk_bf16_f32 v73, v182, v184
	v_cvt_pk_bf16_f32 v74, v224, v226
	v_cvt_pk_bf16_f32 v75, v228, v230
	v_max3_f32 v57, v96, v97, v98
	v_max3_f32 v57, v57, v102, v103
	v_max3_f32 v58, v58, v101, v104
	v_cvt_pk_bf16_f32 v76, v179, v181
	v_mfma_f32_32x32x16_bf16 v[112:127], v[204:207], v[142:145], v[112:127]
	v_cvt_pk_bf16_f32 v77, v183, v185
	v_cvt_pk_bf16_f32 v78, v225, v227
	v_cvt_pk_bf16_f32 v79, v229, v231
	v_add_f32_e32 v176, v176, v56
	s_waitcnt lgkmcnt(2)
	v_mfma_f32_32x32x16_bf16 v[16:31], v[48:51], v[72:75], v[16:31]
	s_nop 5
	v_max3_f32 v59, v112, v113, v114
	v_max3_f32 v48, v115, v116, v117
	v_max3_f32 v59, v59, v118, v119
	v_max3_f32 v60, v48, v120, v121
	ds_read_b64_tr_b16 v[48:49], v175 offset:27648
	ds_read_b64_tr_b16 v[50:51], v175 offset:29184
	s_waitcnt lgkmcnt(2)
	v_mfma_f32_32x32x16_bf16 v[0:15], v[52:55], v[72:75], v[0:15]
	v_max3_f32 v52, v57, v106, v107
	v_max3_f32 v57, v58, v105, v108
	v_max3_f32 v58, v59, v122, v123
	v_max3_f32 v59, v60, v124, v125
	v_max3_f32 v60, v52, v110, v111
	ds_read_b64_tr_b16 v[54:55], v175 offset:29248
	ds_read_b64_tr_b16 v[52:53], v175 offset:27712
	s_waitcnt lgkmcnt(2)
	v_mfma_f32_32x32x16_bf16 v[16:31], v[48:51], v[76:79], v[16:31]
	v_max3_f32 v48, v58, v126, v127
	v_max3_f32 v49, v57, v109, v59
	v_max3_f32 v48, v60, v48, v49
	v_mov_b32_e32 v49, v48
	s_nop 1
	v_permlane32_swap_b32_e32 v48, v49
	v_max_f32_e32 v49, v49, v49
	s_waitcnt lgkmcnt(0)
	v_mfma_f32_32x32x16_bf16 v[0:15], v[52:55], v[76:79], v[0:15]
	v_max_f32_e32 v48, v48, v48
	v_max_f32_e32 v48, v48, v49
	v_cmp_lt_f32_e32 vcc, s51, v48
	s_cbranch_vccnz .LBB0_1770
	v_cndmask_b32_e64 v48, 0, 1, s[40:41]
	v_cmp_ne_u32_e64 s[2:3], 1, v48
	s_andn2_b64 vcc, exec, s[40:41]
	s_cbranch_vccnz .LBB0_1760

.LBB0_1760:
	s_cmpk_lt_u32 s44, 0x41
	s_cselect_b64 s[40:41], -1, 0
	s_cmp_gt_u32 s44, 64
	s_waitcnt vmcnt(0)
	ds_write_b128 v167, v[150:153] offset:30720
	s_waitcnt lgkmcnt(0)
	s_cbranch_scc1 .LBB0_1762
	v_add_co_u32_e32 v48, vcc, 0x6e10000, v160
	s_nop 1
	v_addc_co_u32_e32 v49, vcc, 0, v161, vcc
	global_load_dwordx4 v[146:149], v[48:49], off offset:1856

.LBB0_1764:
	s_barrier
	ds_read_b128 v[64:67], v165
	ds_read_b128 v[68:71], v165 offset:32
	ds_read_b128 v[72:75], v165 offset:4608
	ds_read_b128 v[76:79], v165 offset:4640
	v_exp_f32_e32 v196, v96
	s_waitcnt lgkmcnt(3)
	v_mfma_f32_32x32x16_bf16 v[48:63], v[64:67], v[130:133], v[32:47]
	ds_read_b128 v[64:67], v165 offset:64
	ds_read_b128 v[160:163], v165 offset:96
	ds_read_b128 v[178:181], v165 offset:4672
	ds_read_b128 v[182:185], v165 offset:4704
	v_exp_f32_e32 v198, v97
	v_exp_f32_e32 v200, v98
	v_exp_f32_e32 v202, v99
	v_exp_f32_e32 v204, v100
	v_exp_f32_e32 v206, v101
	v_exp_f32_e32 v208, v102
	s_waitcnt lgkmcnt(5)
	v_mfma_f32_32x32x16_bf16 v[80:95], v[72:75], v[130:133], v[32:47]
	v_exp_f32_e32 v210, v103
	v_exp_f32_e32 v197, v104
	v_exp_f32_e32 v199, v105
	v_exp_f32_e32 v201, v106
	v_exp_f32_e32 v203, v107
	v_exp_f32_e32 v205, v108
	v_exp_f32_e32 v207, v109
	s_waitcnt lgkmcnt(4)
	v_mfma_f32_32x32x16_bf16 v[80:95], v[76:79], v[134:137], v[80:95]
	v_exp_f32_e32 v209, v110
	v_exp_f32_e32 v211, v111
	ds_read_b64_tr_b16 v[96:97], v175 offset:30720
	ds_read_b64_tr_b16 v[98:99], v175 offset:32256
	ds_read_b64_tr_b16 v[102:103], v175 offset:32320
	ds_read_b64_tr_b16 v[100:101], v175 offset:30784
	ds_read_b64_tr_b16 v[104:105], v175 offset:33792
	ds_read_b64_tr_b16 v[106:107], v175 offset:35328
	ds_read_b64_tr_b16 v[110:111], v175 offset:35392
	ds_read_b64_tr_b16 v[108:109], v175 offset:33856
	v_exp_f32_e32 v112, v112
	v_exp_f32_e32 v212, v113
	v_exp_f32_e32 v114, v114
	v_exp_f32_e32 v214, v115
	v_mfma_f32_32x32x16_bf16 v[48:63], v[68:71], v[134:137], v[48:63]
	v_exp_f32_e32 v113, v120
	v_exp_f32_e32 v213, v121
	v_exp_f32_e32 v115, v122
	v_exp_f32_e32 v215, v123
	v_exp_f32_e32 v116, v116
	v_exp_f32_e32 v216, v117
	v_exp_f32_e32 v118, v118
	s_waitcnt lgkmcnt(8)
	v_mfma_f32_32x32x16_bf16 v[80:95], v[178:181], v[138:141], v[80:95]
	v_mfma_f32_32x32x16_bf16 v[48:63], v[64:67], v[138:141], v[48:63]
	v_mfma_f32_32x32x16_bf16 v[64:79], v[182:185], v[142:145], v[80:95]
	v_mfma_f32_32x32x16_bf16 v[48:63], v[160:163], v[142:145], v[48:63]
	v_exp_f32_e32 v218, v119
	v_exp_f32_e32 v117, v124
	v_exp_f32_e32 v217, v125
	v_exp_f32_e32 v119, v126
	v_exp_f32_e32 v219, v127
	v_pk_add_f32 v[120:121], v[208:209], v[210:211]
	s_and_b64 vcc, exec, s[2:3]
	s_nop 1
	v_cvt_pk_bf16_f32 v80, v196, v198
	v_cvt_pk_bf16_f32 v81, v200, v202
	v_cvt_pk_bf16_f32 v82, v204, v206
	v_cvt_pk_bf16_f32 v83, v208, v210
	v_cvt_pk_bf16_f32 v84, v197, v199
	v_cvt_pk_bf16_f32 v85, v201, v203
	v_cvt_pk_bf16_f32 v86, v205, v207
	v_cvt_pk_bf16_f32 v87, v209, v211
	v_cvt_pk_bf16_f32 v88, v112, v212
	v_cvt_pk_bf16_f32 v89, v114, v214
	v_cvt_pk_bf16_f32 v90, v116, v216
	s_waitcnt lgkmcnt(6)
	v_mfma_f32_32x32x16_bf16 v[16:31], v[96:99], v[80:83], v[16:31]
	v_add_f32_e64 v96, v196, v198
	v_add_f32_e64 v97, v197, v199
	v_add_f32_e64 v98, v200, v202
	v_add_f32_e64 v99, v201, v203
	v_cvt_pk_bf16_f32 v91, v118, v218
	v_pk_add_f32 v[96:97], v[96:97], v[98:99]
	v_pk_add_f32 v[98:99], v[204:205], v[206:207]
	v_pk_add_f32 v[98:99], v[98:99], v[120:121]
	s_waitcnt lgkmcnt(4)
	v_mfma_f32_32x32x16_bf16 v[0:15], v[100:103], v[80:83], v[0:15]
	v_add_f32_e64 v80, v98, 0
	v_add_f32_e64 v81, v99, 0
	v_add_f32_e64 v82, v112, v212
	v_add_f32_e64 v83, v113, v213
	v_add_f32_e64 v98, v114, v214
	v_add_f32_e64 v99, v115, v215
	v_pk_add_f32 v[100:101], v[118:119], v[218:219]
	v_pk_add_f32 v[82:83], v[82:83], v[98:99]
	v_pk_add_f32 v[98:99], v[116:117], v[216:217]
	v_pk_add_f32 v[82:83], v[82:83], v[96:97]
	v_add_f32_e64 v98, v98, v100
	v_add_f32_e64 v99, v99, v101
	v_max3_f32 v97, v48, v49, v50
	v_add_f32_e64 v80, v98, v80
	v_add_f32_e64 v81, v99, v81
	v_cvt_pk_bf16_f32 v92, v113, v213
	v_pk_add_f32 v[80:81], v[82:83], v[80:81]
	v_cvt_pk_bf16_f32 v93, v115, v215
	v_add_f32_e32 v96, v80, v81
	s_waitcnt lgkmcnt(2)
	v_mfma_f32_32x32x16_bf16 v[16:31], v[104:107], v[84:87], v[16:31]
	ds_read_b64_tr_b16 v[80:81], v175 offset:36864
	ds_read_b64_tr_b16 v[82:83], v175 offset:38400
	v_max3_f32 v99, v64, v65, v66
	v_max3_f32 v100, v67, v68, v69
	v_cvt_pk_bf16_f32 v94, v117, v217
	v_cvt_pk_bf16_f32 v95, v119, v219
	v_add_f32_e32 v176, v176, v96
	s_waitcnt lgkmcnt(2)
	v_mfma_f32_32x32x16_bf16 v[0:15], v[108:111], v[84:87], v[0:15]
	v_max_f32_e32 v98, v51, v52
	ds_read_b64_tr_b16 v[86:87], v175 offset:38464
	ds_read_b64_tr_b16 v[84:85], v175 offset:36928
	s_waitcnt lgkmcnt(2)
	v_mfma_f32_32x32x16_bf16 v[16:31], v[80:83], v[88:91], v[16:31]
	v_max3_f32 v80, v97, v54, v55
	v_max3_f32 v97, v98, v53, v56
	v_max3_f32 v98, v99, v70, v71
	v_max3_f32 v99, v100, v72, v73
	v_max3_f32 v100, v80, v58, v59
	ds_read_b64_tr_b16 v[80:81], v175 offset:39936
	ds_read_b64_tr_b16 v[82:83], v175 offset:41472
	s_waitcnt lgkmcnt(2)
	v_mfma_f32_32x32x16_bf16 v[0:15], v[84:87], v[88:91], v[0:15]
	v_max3_f32 v84, v98, v74, v75
	v_max3_f32 v91, v84, v78, v79
	ds_read_b64_tr_b16 v[86:87], v175 offset:41536
	ds_read_b64_tr_b16 v[84:85], v175 offset:40000
	v_max3_f32 v88, v97, v57, v60
	v_max3_f32 v89, v99, v76, v77
	v_max3_f32 v90, v100, v62, v63
	s_waitcnt lgkmcnt(2)
	v_mfma_f32_32x32x16_bf16 v[16:31], v[80:83], v[92:95], v[16:31]
	v_max3_f32 v80, v88, v61, v89
	v_max3_f32 v80, v90, v91, v80
	v_mov_b32_e32 v81, v80
	s_nop 1
	v_permlane32_swap_b32_e32 v80, v81
	s_waitcnt lgkmcnt(0)
	v_mfma_f32_32x32x16_bf16 v[0:15], v[84:87], v[92:95], v[0:15]
	s_cbranch_vccnz .LBB0_1766
	v_max_f32_e32 v80, v80, v81
	v_cmp_lt_f32_e32 vcc, s51, v80
	s_cbranch_vccnz .LBB0_1771

.LBB0_1837:
	v_bfe_u32 v0, v28, 2, 2
	v_lshl_or_b32 v0, v29, 2, v0
	v_mad_u32_u24 v4, v0, s49, 0
	v_and_b32_e32 v0, 16, v28
	v_lshlrev_b32_e32 v1, 2, v28
	v_mov_b32_e32 v37, v129
	v_lshl_add_u64 v[2:3], s[14:15], 0, v[34:35]
	v_and_or_b32 v0, v1, 12, v0
	s_mul_i32 s42, s42, 0xee0000
	v_lshl_add_u64 v[178:179], v[36:37], 1, v[2:3]
	v_lshlrev_b64 v[2:3], 12, v[174:175]
	v_lshlrev_b32_e32 v5, 1, v0
	v_subrev_u32_e32 v0, 64, v40
	v_mov_b32_e32 v1, v129
	v_lshl_add_u64 v[2:3], s[14:15], 0, v[2:3]
	s_or_b32 s14, s13, s42
	v_ashrrev_i32_e32 v41, 31, v40
	v_lshl_add_u64 v[180:181], v[0:1], 1, v[2:3]
	v_lshl_add_u64 v[0:1], s[14:15], 0, v[90:91]
	v_lshl_add_u64 v[130:131], v[30:31], 1, s[8:9]
	v_cmp_gt_i32_e64 s[6:7], 8, v38
	v_lshl_add_u64 v[176:177], v[40:41], 1, s[8:9]
	v_add_u32_e32 v205, 0, v33
	v_lshl_add_u64 v[182:183], v[0:1], 0, v[128:129]
	v_add_u32_e32 v175, v4, v5
	v_mov_b32_e32 v33, v32
	v_mov_b32_e32 v34, v32
	v_mov_b32_e32 v35, v32
	v_mov_b32_e32 v36, v32
	v_mov_b32_e32 v37, v32
	v_mov_b32_e32 v38, v32
	v_mov_b32_e32 v39, v32
	v_mov_b32_e32 v40, v32
	v_mov_b32_e32 v41, v32
	v_mov_b32_e32 v42, v32
	v_mov_b32_e32 v43, v32
	v_mov_b32_e32 v44, v32
	v_mov_b32_e32 v45, v32
	v_mov_b32_e32 v46, v32
	v_mov_b32_e32 v47, v32
	v_mov_b32_e32 v16, v206
	v_mov_b32_e32 v17, v206
	v_mov_b32_e32 v18, v206
	v_mov_b32_e32 v19, v206
	v_mov_b32_e32 v20, v206
	v_mov_b32_e32 v21, v206
	v_mov_b32_e32 v22, v206
	v_mov_b32_e32 v23, v206
	v_mov_b32_e32 v24, v206
	v_mov_b32_e32 v25, v206
	v_mov_b32_e32 v26, v206
	v_mov_b32_e32 v27, v206
	v_mov_b32_e32 v28, v206
	v_mov_b32_e32 v29, v206
	v_mov_b32_e32 v30, v206
	v_mov_b32_e32 v31, v206
	v_mov_b32_e32 v0, v206
	v_mov_b32_e32 v1, v206
	v_mov_b32_e32 v2, v206
	v_mov_b32_e32 v3, v206
	v_mov_b32_e32 v4, v206
	v_mov_b32_e32 v5, v206
	v_mov_b32_e32 v6, v206
	v_mov_b32_e32 v7, v206
	v_mov_b32_e32 v8, v206
	v_mov_b32_e32 v9, v206
	v_mov_b32_e32 v10, v206
	v_mov_b32_e32 v11, v206
	v_mov_b32_e32 v12, v206
	v_mov_b32_e32 v13, v206
	v_mov_b32_e32 v14, v206
	v_mov_b32_e32 v15, v206
	s_add_i32 s14, s20, 2
	s_lshl_b32 s14, s14, 6
	v_add_u32_e32 v82, s14, v172
	v_mad_i64_i32 v[82:83], s[24:25], v82, s67, v[130:131]
	v_lshl_add_u64 v[82:83], v[82:83], 0, s[18:19]
	v_lshl_add_u64 v[80:81], s[74:75], 0, v[178:179]
	v_lshl_add_u64 v[80:81], v[80:81], 0, s[34:35]
	v_cndmask_b32_e64 v130, v80, v82, s[2:3]
	v_cndmask_b32_e64 v131, v81, v83, s[2:3]
	v_mov_b32_e32 v178, 0x40000
	v_mov_b32_e32 v80, 0x38000
	v_cndmask_b32_e64 v178, v178, v80, s[2:3]
	v_add_u32_e32 v82, s14, v174
	v_mad_i64_i32 v[82:83], s[24:25], v82, s67, v[176:177]
	v_lshl_add_u64 v[82:83], v[82:83], 0, s[18:19]
	v_lshl_add_u64 v[80:81], s[74:75], 0, v[180:181]
	v_lshl_add_u64 v[80:81], v[80:81], 0, s[34:35]
	v_cndmask_b32_e64 v176, v80, v82, s[6:7]
	v_cndmask_b32_e64 v177, v81, v83, s[6:7]
	v_mov_b32_e32 v180, 0x40000
	v_mov_b32_e32 v80, 0x38000
	v_cndmask_b32_e64 v180, v180, v80, s[6:7]
.LBB0_1838:
	s_add_i32 s13, s20, 2
	s_cmpk_lt_u32 s20, 0x42
	s_cselect_b64 s[40:41], -1, 0
	s_cmpk_gt_u32 s20, 0x41
	s_cselect_b64 s[38:39], -1, 0
	s_and_b64 vcc, exec, s[38:39]
	s_cbranch_vccnz .LBB0_1850
	global_load_dwordx4 v[132:135], v[130:131], off
	v_add_co_u32_e32 v130, vcc, v178, v130
	s_nop 1
	v_addc_co_u32_e32 v131, vcc, 0, v131, vcc
	s_and_saveexec_b64 s[8:9], s[4:5]
	s_cbranch_execz .Lm0b_s1
	global_load_dwordx4 v[136:139], v[176:177], off
	v_add_co_u32_e32 v176, vcc, v180, v176
	s_nop 1
	v_addc_co_u32_e32 v177, vcc, 0, v177, vcc

.LBB0_1850:
	s_barrier
	ds_read_b128 v[80:83], v203 offset:13312
	ds_read_b128 v[84:87], v203 offset:13344
	s_waitcnt vmcnt(0)
	ds_read_b128 v[164:167], v203 offset:19968
	ds_read_b128 v[208:211], v203 offset:20000
	ds_read_b128 v[212:215], v203 offset:13376
	v_lshl_add_u64 v[184:185], s[74:75], 0, v[182:183]
	s_waitcnt lgkmcnt(4)
	v_mfma_f32_32x32x16_bf16 v[96:111], v[80:83], v[140:143], v[32:47]
	ds_read_b128 v[216:219], v203 offset:13408
	v_exp_f32_e32 v220, v48
	v_exp_f32_e32 v222, v49
	v_exp_f32_e32 v224, v50
	v_exp_f32_e32 v226, v51
	ds_read_b128 v[48:51], v203 offset:20064
	v_exp_f32_e32 v228, v52
	s_waitcnt lgkmcnt(4)
	v_mfma_f32_32x32x16_bf16 v[112:127], v[164:167], v[140:143], v[32:47]
	v_add_co_u32_e32 v164, vcc, 0xf588000, v184
	v_exp_f32_e32 v230, v53
	s_nop 0
	v_addc_co_u32_e32 v165, vcc, 0, v185, vcc
	global_load_dwordx4 v[164:167], v[164:165], off offset:1664
	v_exp_f32_e32 v232, v54
	v_mfma_f32_32x32x16_bf16 v[96:111], v[84:87], v[144:147], v[96:111]
	v_exp_f32_e32 v234, v55
	v_exp_f32_e32 v221, v56
	v_exp_f32_e32 v223, v57
	v_exp_f32_e32 v225, v58
	v_exp_f32_e32 v227, v59
	v_exp_f32_e32 v229, v60
	v_exp_f32_e32 v231, v61
	s_waitcnt lgkmcnt(2)
	v_mfma_f32_32x32x16_bf16 v[96:111], v[212:215], v[148:151], v[96:111]
	ds_read_b128 v[212:215], v203 offset:20032
	ds_read_b128 v[52:55], v203 offset:13440
	ds_read_b128 v[56:59], v203 offset:13472
	v_exp_f32_e32 v233, v62
	v_exp_f32_e32 v235, v63
	v_exp_f32_e32 v236, v68
	v_exp_f32_e32 v238, v69
	v_exp_f32_e32 v240, v70
	v_mfma_f32_32x32x16_bf16 v[112:127], v[208:211], v[144:147], v[112:127]
	ds_read_b128 v[60:63], v203 offset:20096
	ds_read_b128 v[208:211], v203 offset:20128
	v_exp_f32_e32 v242, v71
	v_cvt_pk_bf16_f32 v68, v220, v222
	v_cvt_pk_bf16_f32 v69, v224, v226
	v_cvt_pk_bf16_f32 v70, v228, v230
	v_cvt_pk_bf16_f32 v71, v232, v234
	v_exp_f32_e32 v237, v76
	s_waitcnt lgkmcnt(4)
	v_mfma_f32_32x32x16_bf16 v[112:127], v[212:215], v[148:151], v[112:127]
	v_exp_f32_e32 v212, v64
	v_exp_f32_e32 v214, v65
	v_exp_f32_e32 v213, v72
	v_exp_f32_e32 v215, v73
	v_exp_f32_e32 v239, v77
	v_exp_f32_e32 v241, v78
	v_exp_f32_e32 v243, v79
	v_mfma_f32_32x32x16_bf16 v[96:111], v[216:219], v[152:155], v[96:111]
	v_exp_f32_e32 v216, v66
	v_exp_f32_e32 v218, v67
	v_exp_f32_e32 v217, v74
	v_exp_f32_e32 v219, v75
	v_cvt_pk_bf16_f32 v72, v221, v223
	v_cvt_pk_bf16_f32 v73, v225, v227
	v_cvt_pk_bf16_f32 v74, v229, v231
	v_mfma_f32_32x32x16_bf16 v[112:127], v[48:51], v[152:155], v[112:127]
	v_cvt_pk_bf16_f32 v75, v233, v235
	v_cvt_pk_bf16_f32 v76, v213, v215
	v_cvt_pk_bf16_f32 v77, v217, v219
	v_cvt_pk_bf16_f32 v78, v237, v239
	v_cvt_pk_bf16_f32 v79, v241, v243
	s_waitcnt lgkmcnt(3)
	v_mfma_f32_32x32x16_bf16 v[96:111], v[52:55], v[156:159], v[96:111]
	ds_read_b64_tr_b16 v[48:49], v175 offset:26624
	ds_read_b64_tr_b16 v[50:51], v175 offset:28160
	ds_read_b64_tr_b16 v[54:55], v175 offset:28224
	ds_read_b64_tr_b16 v[52:53], v175 offset:26688
	s_waitcnt lgkmcnt(5)
	v_mfma_f32_32x32x16_bf16 v[112:127], v[60:63], v[156:159], v[112:127]
	ds_read_b64_tr_b16 v[60:61], v175 offset:29696
	ds_read_b64_tr_b16 v[62:63], v175 offset:31232
	ds_read_b64_tr_b16 v[66:67], v175 offset:31296
	ds_read_b64_tr_b16 v[64:65], v175 offset:29760
	s_waitcnt lgkmcnt(6)
	v_mfma_f32_32x32x16_bf16 v[16:31], v[48:51], v[68:71], v[16:31]
	v_add_f32_e64 v48, v228, v230
	v_add_f32_e64 v49, v229, v231
	v_add_f32_e64 v50, v232, v234
	v_add_f32_e64 v51, v233, v235
	v_add_f32_e64 v48, v48, v50
	v_add_f32_e64 v49, v49, v51
	s_waitcnt lgkmcnt(4)
	v_mfma_f32_32x32x16_bf16 v[0:15], v[52:55], v[68:71], v[0:15]
	v_add_f32_e64 v54, v236, v238
	v_add_f32_e64 v55, v237, v239
	v_add_f32_e64 v68, v240, v242
	v_add_f32_e64 v69, v241, v243
	v_add_f32_e64 v54, v54, v68
	v_add_f32_e64 v55, v55, v69
	v_pk_add_f32 v[48:49], v[48:49], v[54:55]
	v_mfma_f32_32x32x16_bf16 v[96:111], v[56:59], v[160:163], v[96:111]
	v_cvt_pk_bf16_f32 v56, v212, v214
	v_cvt_pk_bf16_f32 v57, v216, v218
	v_cvt_pk_bf16_f32 v58, v236, v238
	v_cvt_pk_bf16_f32 v59, v240, v242
	v_mfma_f32_32x32x16_bf16 v[112:127], v[208:211], v[160:163], v[112:127]
	v_add_f32_e64 v208, v220, v222
	v_add_f32_e64 v209, v221, v223
	v_add_f32_e64 v210, v224, v226
	v_add_f32_e64 v211, v225, v227
	v_add_f32_e64 v208, v208, v210
	v_add_f32_e64 v209, v209, v211
	v_pk_add_f32 v[210:211], v[216:217], v[218:219]
	v_pk_add_f32 v[50:51], v[208:209], 0 op_sel_hi:[1,0]
	v_pk_add_f32 v[208:209], v[212:213], v[214:215]
	s_waitcnt lgkmcnt(2)
	v_mfma_f32_32x32x16_bf16 v[16:31], v[60:63], v[72:75], v[16:31]
	v_add_f32_e64 v52, v208, v210
	v_add_f32_e64 v53, v209, v211
	v_max3_f32 v54, v112, v113, v114
	v_add_f32_e64 v50, v50, v52
	v_add_f32_e64 v51, v51, v53
	v_max3_f32 v52, v96, v97, v98
	v_pk_add_f32 v[48:49], v[50:51], v[48:49]
	v_max3_f32 v62, v52, v102, v103
	v_add_f32_e32 v60, v48, v49
	s_waitcnt lgkmcnt(0)
	v_mfma_f32_32x32x16_bf16 v[0:15], v[64:67], v[72:75], v[0:15]
	v_max_f32_e32 v53, v99, v100
	ds_read_b64_tr_b16 v[48:49], v175 offset:32768
	ds_read_b64_tr_b16 v[50:51], v175 offset:34304
	v_max3_f32 v63, v53, v101, v104
	v_max3_f32 v64, v54, v118, v119
	ds_read_b64_tr_b16 v[54:55], v175 offset:34368
	ds_read_b64_tr_b16 v[52:53], v175 offset:32832
	v_max3_f32 v61, v115, v116, v117
	s_waitcnt lgkmcnt(2)
	v_mfma_f32_32x32x16_bf16 v[16:31], v[48:51], v[56:59], v[16:31]
	v_max3_f32 v48, v61, v120, v121
	v_max3_f32 v61, v62, v106, v107
	v_max3_f32 v62, v63, v105, v108
	v_max3_f32 v63, v64, v122, v123
	v_max3_f32 v64, v48, v124, v125
	ds_read_b64_tr_b16 v[48:49], v175 offset:35840
	ds_read_b64_tr_b16 v[50:51], v175 offset:37376
	v_add_f32_e32 v206, v206, v60
	s_waitcnt lgkmcnt(2)
	v_mfma_f32_32x32x16_bf16 v[0:15], v[52:55], v[56:59], v[0:15]
	v_max3_f32 v52, v61, v110, v111
	v_max3_f32 v53, v63, v126, v127
	v_max3_f32 v54, v62, v109, v64
	v_max3_f32 v56, v52, v53, v54
	ds_read_b64_tr_b16 v[54:55], v175 offset:37440
	ds_read_b64_tr_b16 v[52:53], v175 offset:35904
	v_mov_b32_e32 v57, v56
	s_nop 1
	v_permlane32_swap_b32_e32 v56, v57
	s_waitcnt lgkmcnt(2)
	v_mfma_f32_32x32x16_bf16 v[16:31], v[48:51], v[76:79], v[16:31]
	v_max_f32_e32 v48, v57, v57
	v_max_f32_e32 v49, v56, v56
	v_max_f32_e32 v48, v49, v48
	v_cmp_lt_f32_e32 vcc, s51, v48
	s_waitcnt lgkmcnt(0)
	v_mfma_f32_32x32x16_bf16 v[0:15], v[52:55], v[76:79], v[0:15]
	s_cbranch_vccnz .LBB0_1879
	v_cndmask_b32_e64 v48, 0, 1, s[40:41]
	v_cmp_ne_u32_e64 s[8:9], 1, v48
	s_andn2_b64 vcc, exec, s[40:41]
	s_cbranch_vccnz .LBB0_1855

.LBB0_1855:
	s_cmpk_lt_u32 s20, 0x41
	s_cselect_b64 s[40:41], -1, 0
	s_cmp_gt_u32 s20, 64
	s_waitcnt vmcnt(0)
	ds_write_b128 v202, v[164:167] offset:38912
	s_waitcnt lgkmcnt(0)
	s_cbranch_scc1 .LBB0_1867
	global_load_dwordx4 v[132:135], v[130:131], off
	v_add_co_u32_e32 v130, vcc, v178, v130
	s_nop 1
	v_addc_co_u32_e32 v131, vcc, 0, v131, vcc
	s_and_saveexec_b64 s[42:43], s[4:5]
	s_cbranch_execz .Lm0b_s2
	global_load_dwordx4 v[136:139], v[176:177], off
	v_add_co_u32_e32 v176, vcc, v180, v176
	s_nop 1
	v_addc_co_u32_e32 v177, vcc, 0, v177, vcc

.LBB0_1869:
	s_barrier
	ds_read_b128 v[64:67], v203
	ds_read_b128 v[68:71], v203 offset:32
	v_exp_f32_e32 v184, v96
	v_exp_f32_e32 v208, v97
	v_exp_f32_e32 v210, v98
	s_waitcnt lgkmcnt(1)
	v_mfma_f32_32x32x16_bf16 v[48:63], v[64:67], v[140:143], v[32:47]
	v_exp_f32_e32 v212, v99
	v_exp_f32_e32 v214, v100
	v_exp_f32_e32 v216, v101
	v_exp_f32_e32 v218, v102
	v_exp_f32_e32 v220, v103
	v_exp_f32_e32 v185, v104
	v_exp_f32_e32 v209, v105
	s_waitcnt lgkmcnt(0)
	v_mfma_f32_32x32x16_bf16 v[48:63], v[68:71], v[144:147], v[48:63]
	ds_read_b128 v[64:67], v203 offset:6656
	ds_read_b128 v[68:71], v203 offset:6688
	v_exp_f32_e32 v211, v106
	v_exp_f32_e32 v213, v107
	v_exp_f32_e32 v215, v108
	v_exp_f32_e32 v217, v109
	v_exp_f32_e32 v219, v110
	v_exp_f32_e32 v221, v111
	s_waitcnt lgkmcnt(1)
	v_mfma_f32_32x32x16_bf16 v[80:95], v[64:67], v[140:143], v[32:47]
	ds_read_b128 v[64:67], v203 offset:64
	ds_read_b128 v[72:75], v203 offset:96
	v_exp_f32_e32 v222, v112
	v_exp_f32_e32 v224, v113
	v_exp_f32_e32 v226, v114
	v_exp_f32_e32 v228, v115
	v_exp_f32_e32 v230, v116
	v_exp_f32_e32 v232, v117
	s_waitcnt lgkmcnt(1)
	v_mfma_f32_32x32x16_bf16 v[48:63], v[64:67], v[148:151], v[48:63]
	ds_read_b128 v[64:67], v203 offset:6720
	v_exp_f32_e32 v234, v118
	v_exp_f32_e32 v236, v119
	v_exp_f32_e32 v223, v120
	v_exp_f32_e32 v225, v121
	v_exp_f32_e32 v227, v122
	v_exp_f32_e32 v229, v123
	v_mfma_f32_32x32x16_bf16 v[80:95], v[68:71], v[144:147], v[80:95]
	ds_read_b128 v[68:71], v203 offset:6752
	v_exp_f32_e32 v231, v124
	v_exp_f32_e32 v233, v125
	v_exp_f32_e32 v235, v126
	v_exp_f32_e32 v237, v127
	s_and_b64 vcc, exec, s[8:9]
	s_waitcnt lgkmcnt(1)
	v_mfma_f32_32x32x16_bf16 v[80:95], v[64:67], v[148:151], v[80:95]
	s_waitcnt lgkmcnt(0)
	v_mfma_f32_32x32x16_bf16 v[80:95], v[68:71], v[152:155], v[80:95]
	v_mfma_f32_32x32x16_bf16 v[48:63], v[72:75], v[152:155], v[48:63]
	ds_read_b128 v[64:67], v203 offset:128
	ds_read_b128 v[96:99], v203 offset:160
	ds_read_b128 v[72:75], v203 offset:6784
	ds_read_b128 v[100:103], v203 offset:6816
	ds_read_b64_tr_b16 v[104:105], v175 offset:38912
	ds_read_b64_tr_b16 v[106:107], v175 offset:40448
	ds_read_b64_tr_b16 v[110:111], v175 offset:40512
	ds_read_b64_tr_b16 v[108:109], v175 offset:38976
	ds_read_b64_tr_b16 v[112:113], v175 offset:41984
	ds_read_b64_tr_b16 v[114:115], v175 offset:43520
	ds_read_b64_tr_b16 v[118:119], v175 offset:43584
	ds_read_b64_tr_b16 v[116:117], v175 offset:42048
	s_waitcnt lgkmcnt(8)
	v_mfma_f32_32x32x16_bf16 v[80:95], v[72:75], v[156:159], v[80:95]
	v_mfma_f32_32x32x16_bf16 v[48:63], v[64:67], v[156:159], v[48:63]
	v_mfma_f32_32x32x16_bf16 v[64:79], v[100:103], v[160:163], v[80:95]
	v_mfma_f32_32x32x16_bf16 v[48:63], v[96:99], v[160:163], v[48:63]
	v_add_f32_e64 v96, v184, v208
	v_add_f32_e64 v97, v185, v209
	v_add_f32_e64 v98, v210, v212
	v_add_f32_e64 v99, v211, v213
	v_pk_add_f32 v[96:97], v[96:97], v[98:99]
	v_pk_add_f32 v[98:99], v[214:215], v[216:217]
	s_nop 2
	v_cvt_pk_bf16_f32 v80, v184, v208
	v_cvt_pk_bf16_f32 v81, v210, v212
	v_cvt_pk_bf16_f32 v82, v214, v216
	v_cvt_pk_bf16_f32 v83, v218, v220
	v_cvt_pk_bf16_f32 v84, v185, v209
	v_cvt_pk_bf16_f32 v85, v211, v213
	v_cvt_pk_bf16_f32 v86, v215, v217
	s_waitcnt lgkmcnt(6)
	v_mfma_f32_32x32x16_bf16 v[16:31], v[104:107], v[80:83], v[16:31]
	v_cvt_pk_bf16_f32 v87, v219, v221
	v_add_f32_e64 v96, v96, 0
	v_add_f32_e64 v97, v97, 0
	v_cvt_pk_bf16_f32 v88, v222, v224
	v_cvt_pk_bf16_f32 v89, v226, v228
	v_cvt_pk_bf16_f32 v90, v230, v232
	v_cvt_pk_bf16_f32 v91, v234, v236
	v_cvt_pk_bf16_f32 v92, v223, v225
	s_waitcnt lgkmcnt(4)
	v_mfma_f32_32x32x16_bf16 v[0:15], v[108:111], v[80:83], v[0:15]
	v_add_f32_e64 v82, v222, v224
	v_add_f32_e64 v83, v223, v225
	v_cvt_pk_bf16_f32 v93, v227, v229
	v_cvt_pk_bf16_f32 v94, v231, v233
	v_cvt_pk_bf16_f32 v95, v235, v237
	v_add_f32_e64 v100, v218, v220
	v_add_f32_e64 v101, v219, v221
	v_add_f32_e64 v98, v98, v100
	v_add_f32_e64 v99, v99, v101
	v_add_f32_e64 v100, v234, v236
	v_add_f32_e64 v101, v235, v237
	v_pk_add_f32 v[80:81], v[98:99], 0 op_sel_hi:[1,0]
	v_pk_add_f32 v[98:99], v[226:227], v[228:229]
	s_nop 0
	v_pk_add_f32 v[82:83], v[82:83], v[98:99]
	v_pk_add_f32 v[98:99], v[230:231], v[232:233]
	s_waitcnt lgkmcnt(2)
	v_mfma_f32_32x32x16_bf16 v[16:31], v[112:115], v[84:87], v[16:31]
	v_add_f32_e64 v98, v98, v100
	v_add_f32_e64 v99, v99, v101
	v_add_f32_e64 v82, v82, v96
	v_add_f32_e64 v83, v83, v97
	v_add_f32_e64 v80, v98, v80
	v_add_f32_e64 v81, v99, v81
	v_max3_f32 v97, v48, v49, v50
	v_pk_add_f32 v[80:81], v[82:83], v[80:81]
	v_max3_f32 v99, v64, v65, v66
	v_add_f32_e32 v96, v80, v81
	s_waitcnt lgkmcnt(0)
	v_mfma_f32_32x32x16_bf16 v[0:15], v[116:119], v[84:87], v[0:15]
	ds_read_b64_tr_b16 v[80:81], v175 offset:45056
	ds_read_b64_tr_b16 v[82:83], v175 offset:46592
	v_max_f32_e32 v98, v51, v52
	ds_read_b64_tr_b16 v[86:87], v175 offset:46656
	ds_read_b64_tr_b16 v[84:85], v175 offset:45120
	v_max3_f32 v100, v67, v68, v69
	v_add_f32_e32 v206, v206, v96
	s_waitcnt lgkmcnt(2)
	v_mfma_f32_32x32x16_bf16 v[16:31], v[80:83], v[88:91], v[16:31]
	v_max3_f32 v80, v97, v54, v55
	v_max3_f32 v97, v98, v53, v56
	v_max3_f32 v98, v99, v70, v71
	v_max3_f32 v99, v100, v72, v73
	v_max3_f32 v100, v80, v58, v59
	ds_read_b64_tr_b16 v[80:81], v175 offset:48128
	ds_read_b64_tr_b16 v[82:83], v175 offset:49664
	s_waitcnt lgkmcnt(2)
	v_mfma_f32_32x32x16_bf16 v[0:15], v[84:87], v[88:91], v[0:15]
	v_max3_f32 v84, v98, v74, v75
	v_max3_f32 v91, v84, v78, v79
	ds_read_b64_tr_b16 v[86:87], v175 offset:49728
	ds_read_b64_tr_b16 v[84:85], v175 offset:48192
	v_max3_f32 v88, v97, v57, v60
	v_max3_f32 v89, v99, v76, v77
	v_max3_f32 v90, v100, v62, v63
	s_waitcnt lgkmcnt(2)
	v_mfma_f32_32x32x16_bf16 v[16:31], v[80:83], v[92:95], v[16:31]
	v_max3_f32 v80, v88, v61, v89
	v_max3_f32 v80, v90, v91, v80
	v_mov_b32_e32 v81, v80
	s_nop 1
	v_permlane32_swap_b32_e32 v80, v81
	s_waitcnt lgkmcnt(0)
	v_mfma_f32_32x32x16_bf16 v[0:15], v[84:87], v[92:95], v[0:15]
	s_cbranch_vccnz .LBB0_1871
	v_max_f32_e32 v80, v80, v81
	v_cmp_lt_f32_e32 vcc, s51, v80
	s_cbranch_vccnz .LBB0_1880

.LBB0_1877:
	s_mov_b64 s[8:9], 0x70000
	s_andn2_b64 vcc, exec, s[38:39]
	v_lshl_add_u64 v[182:183], v[182:183], 0, s[8:9]
	s_waitcnt lgkmcnt(0)
	s_cbranch_vccnz .Lrot0b_c
	s_barrier
	s_branch .LBB0_1744
.Lrot0b_c:
	s_mov_b32 s20, s13
	s_branch .LBB0_1838
